# v31: grid barriers: one L2 write-back per XCD (last arriver of the XCC_ID-keyed group) instead of one per workgroup, generation kept in LDS, no top-level counter; chunk-MLP LDS staging without bank co
# speedup vs baseline: 1.7077x; 1.1093x over previous
.LBB0_40:
	s_or_b64 exec, exec, s[0:1]
	s_waitcnt vmcnt(0) lgkmcnt(0)
	v_lshrrev_b32_e32 v1, 20, v0
	v_lshrrev_b32_e32 v0, 10, v0
	v_or_b32_e32 v0, v0, v1
	s_movk_i32 s0, 0x3ff
	v_and_or_b32 v0, v0, s0, v174
	s_barrier
	v_cmp_eq_u32_e64 s[0:1], 0, v0
	s_mov_b64 s[4:5], exec
	s_nop 0
	v_writelane_b32 v255, s0, 28
	s_nop 1
	v_writelane_b32 v255, s1, 29
	v_cmp_gt_u32_e64 s[0:1], 64, v174
	s_nop 1
	v_writelane_b32 v255, s0, 30
	s_nop 1
	v_writelane_b32 v255, s1, 31
	s_and_b64 s[0:1], s[4:5], s[0:1]
	s_mov_b64 exec, s[0:1]
	s_cbranch_execz .Lgs1_done
	s_mov_b64 exec, 1
	s_add_u32 s6, s56, 0x2480000
	s_addc_u32 s7, s57, 0
	s_getreg_b32 s8, hwreg(HW_REG_XCC_ID)
	s_and_b32 s8, s8, 7
	s_lshl_b32 s8, s8, 8
	v_mov_b32_e32 v0, s8
	v_mov_b32_e32 v1, 0
	v_mov_b32_e32 v2, 1
	v_readlane_b32 s10, v255, 16
	v_readlane_b32 s11, v255, 17
	global_load_dword v3, v0, s[6:7] offset:2048 sc1
	buffer_wbl2 sc1
	s_load_dwordx2 s[8:9], s[10:11], 0x58
	s_waitcnt vmcnt(0) lgkmcnt(0)
	global_atomic_add v2, v1, v2, s[8:9] offset:32 sc0
	s_waitcnt vmcnt(0)
	v_readfirstlane_b32 s10, v3
	v_readfirstlane_b32 s11, v2
	s_and_b32 s11, s11, 0xffff
	s_cmp_lg_u32 s11, 0xff
	s_cbranch_scc1 .Lgs1_poll
	v_mov_b32_e32 v3, 0x1000
	s_nop 1
	global_atomic_and v2, v1, v1, s[6:7] sc0
	global_atomic_and v2, v1, v1, s[6:7] offset:256 sc0
	global_atomic_and v2, v1, v1, s[6:7] offset:512 sc0
	global_atomic_and v2, v1, v1, s[6:7] offset:768 sc0
	global_atomic_and v2, v1, v1, s[6:7] offset:1024 sc0
	global_atomic_and v2, v1, v1, s[6:7] offset:1280 sc0
	global_atomic_and v2, v1, v1, s[6:7] offset:1536 sc0
	global_atomic_and v2, v1, v1, s[6:7] offset:1792 sc0
	global_atomic_and v2, v3, v1, s[6:7] sc0
	s_waitcnt vmcnt(0)
	v_mov_b32_e32 v2, 0xff00
	v_mov_b32_e32 v3, 1
	s_nop 1
	global_atomic_add v1, v2, s[8:9] offset:32
	global_atomic_add v1, v3, s[6:7] offset:2048
	global_atomic_add v1, v3, s[6:7] offset:2304
	global_atomic_add v1, v3, s[6:7] offset:2560
	global_atomic_add v1, v3, s[6:7] offset:2816
	global_atomic_add v1, v3, s[6:7] offset:3072
	global_atomic_add v1, v3, s[6:7] offset:3328
	global_atomic_add v1, v3, s[6:7] offset:3584
	global_atomic_add v1, v3, s[6:7] offset:3840

.Lgs1_rel:
	s_nop 1
	v_mov_b32_e32 v2, s9
	v_mov_b32_e32 v3, 0x23ff8
	s_nop 0
	ds_write_b32 v3, v2
	s_mov_b64 exec, s[0:1]
	buffer_inv sc1
	s_waitcnt vmcnt(0) lgkmcnt(0)

.LBB0_66:
	s_or_b64 exec, exec, s[6:7]
	s_waitcnt vmcnt(0) lgkmcnt(0)
	s_barrier
	s_mov_b64 s[4:5], exec
	v_readlane_b32 s0, v255, 30
	v_readlane_b32 s1, v255, 31
	s_and_b64 s[0:1], s[4:5], s[0:1]
	s_mov_b64 exec, s[0:1]
	s_cbranch_execz .Lgs2_done
	s_mov_b64 exec, 1
	v_readlane_b32 s6, v255, 40
	v_readlane_b32 s7, v255, 41
	s_getreg_b32 s8, hwreg(HW_REG_XCC_ID)
	s_nop 3
	s_add_u32 s6, s6, 0x2480000
	s_addc_u32 s7, s7, 0
	s_and_b32 s8, s8, 7
	s_lshl_b32 s8, s8, 8
	v_mov_b32_e32 v0, s8
	v_mov_b32_e32 v2, 1
	v_mov_b32_e32 v3, 0x23ff8
	s_nop 1
	ds_read_b32 v3, v3
	global_atomic_add v2, v0, v2, s[6:7] sc0
	s_waitcnt vmcnt(0) lgkmcnt(0)
	v_readfirstlane_b32 s9, v2
	v_readfirstlane_b32 s10, v3
	s_and_b32 s9, s9, 31
	s_add_u32 s10, s10, 8
	s_cmp_lg_u32 s9, 31
	s_cbranch_scc1 .Lgs2_poll
	buffer_wbl2 sc1
	v_mov_b32_e32 v2, 1
	v_mov_b32_e32 v3, 0
	s_waitcnt vmcnt(0)
	global_atomic_add v3, v2, s[6:7] offset:2048
	global_atomic_add v3, v2, s[6:7] offset:2304
	global_atomic_add v3, v2, s[6:7] offset:2560
	global_atomic_add v3, v2, s[6:7] offset:2816
	global_atomic_add v3, v2, s[6:7] offset:3072
	global_atomic_add v3, v2, s[6:7] offset:3328
	global_atomic_add v3, v2, s[6:7] offset:3584
	global_atomic_add v3, v2, s[6:7] offset:3840

.Lgs2_spin:
	global_load_dword v2, v0, s[6:7] offset:2048 sc1
	s_waitcnt vmcnt(0)
	v_readfirstlane_b32 s9, v2
	s_cmp_eq_u32 s9, s10
	s_cbranch_scc1 .Lgs2_rel
	s_add_u32 s11, s11, 1
	s_cmp_lt_u32 s11, 0x8000
	s_cbranch_scc0 .Lgs2_rel
	s_sleep 1
	s_branch .Lgs2_spin
.Lgs2_rel:
	v_mov_b32_e32 v2, s10
	v_mov_b32_e32 v3, 0x23ff8
	s_nop 0
	ds_write_b32 v3, v2
	s_mov_b64 exec, s[0:1]
	buffer_inv sc1
	s_waitcnt vmcnt(0) lgkmcnt(0)

.LBB0_135:
	s_waitcnt vmcnt(0) lgkmcnt(0)
	s_waitcnt vmcnt(0)
	s_barrier
	s_mov_b64 s[4:5], exec
	v_readlane_b32 s0, v255, 30
	v_readlane_b32 s1, v255, 31
	s_and_b64 s[0:1], s[4:5], s[0:1]
	s_mov_b64 exec, s[0:1]
	s_cbranch_execz .Lgs3_done
	s_mov_b64 exec, 1
	v_readlane_b32 s6, v255, 40
	v_readlane_b32 s7, v255, 41
	s_getreg_b32 s8, hwreg(HW_REG_XCC_ID)
	s_nop 3
	s_add_u32 s6, s6, 0x2480000
	s_addc_u32 s7, s7, 0
	s_and_b32 s8, s8, 7
	s_lshl_b32 s8, s8, 8
	v_mov_b32_e32 v0, s8
	v_mov_b32_e32 v2, 1
	v_mov_b32_e32 v3, 0x23ff8
	s_nop 1
	ds_read_b32 v3, v3
	global_atomic_add v2, v0, v2, s[6:7] sc0
	s_waitcnt vmcnt(0) lgkmcnt(0)
	v_readfirstlane_b32 s9, v2
	v_readfirstlane_b32 s10, v3
	s_and_b32 s9, s9, 31
	s_add_u32 s10, s10, 8
	s_cmp_lg_u32 s9, 31
	s_cbranch_scc1 .Lgs3_poll
	buffer_wbl2 sc1
	v_mov_b32_e32 v2, 1
	v_mov_b32_e32 v3, 0
	s_waitcnt vmcnt(0)
	global_atomic_add v3, v2, s[6:7] offset:2048
	global_atomic_add v3, v2, s[6:7] offset:2304
	global_atomic_add v3, v2, s[6:7] offset:2560
	global_atomic_add v3, v2, s[6:7] offset:2816
	global_atomic_add v3, v2, s[6:7] offset:3072
	global_atomic_add v3, v2, s[6:7] offset:3328
	global_atomic_add v3, v2, s[6:7] offset:3584
	global_atomic_add v3, v2, s[6:7] offset:3840

.LBB0_164:
	s_add_u32 s6, s76, 0x3d00000
	s_addc_u32 s7, s77, 0
	s_add_u32 s8, s76, 0x9100000
	v_ashrrev_i32_e32 v101, 6, v100
	v_bfe_u32 v125, v100, 5, 1
	s_addc_u32 s9, s77, 0
	v_and_b32_e32 v124, 31, v100
	s_cmp_lt_i32 s0, 1
	v_lshlrev_b32_e32 v82, 4, v100
	v_lshlrev_b32_e32 v70, 5, v101
	v_lshlrev_b32_e32 v98, 4, v125
	s_cbranch_scc1 .LBB0_169
	v_cmp_lt_i32_e32 vcc, v183, v177
	s_lshl_b32 s1, s34, 18
	v_ashrrev_i32_e32 v30, 2, v100
	v_cndmask_b32_e32 v0, v176, v183, vcc
	v_cmp_lt_i32_e32 vcc, v182, v177
	v_lshlrev_b32_e32 v31, 2, v0
	s_add_u32 s10, s10, s1
	v_cndmask_b32_e32 v0, v176, v182, vcc
	v_lshlrev_b32_e32 v32, 2, v0
	v_and_b32_e32 v0, 0xffffffe0, v30
	s_addc_u32 s11, s11, 0
	v_ashrrev_i32_e32 v19, 31, v0
	v_or_b32_e32 v18, v0, v124
	v_lshlrev_b32_e32 v0, 5, v125
	v_lshl_add_u64 v[20:21], s[10:11], 0, v[0:1]
	v_and_b32_e32 v0, 32, v70
	s_lshl_b32 s30, s34, 9
	v_or_b32_e32 v3, v0, v124
	v_and_b32_e32 v35, 48, v3
	v_lshlrev_b32_e32 v35, 1, v35
	s_lshl_b64 s[12:13], s[30:31], 2
	v_and_b32_e32 v2, 48, v82
	v_mul_u32_u24_e32 v3, 0x110, v3
	s_add_u32 s4, s4, s12
	v_add3_u32 v33, 0, v3, v98
	v_add_u32_e32 v33, v33, v35
	v_lshl_or_b32 v4, v125, 2, v0
	v_mul_u32_u24_e32 v0, 0x110, v2
	v_lshlrev_b32_e32 v3, 1, v30
	s_addc_u32 s5, s5, s13
	s_mul_i32 s1, s58, 0
	s_add_i32 s2, s58, 0xffffff80
	s_mul_i32 s2, s2, 3
	s_addk_i32 s2, 0x0
	s_cmpk_lt_i32 s58, 0x80
	s_cselect_b32 s1, s1, s2
	s_mov_b32 s2, 0
	v_add3_u32 v34, 0, v0, v3
	v_lshlrev_b32_e32 v0, 1, v2
	v_add_u32_e32 v34, v34, v0
	v_lshlrev_b32_e32 v22, 1, v4
	s_branch .LBB0_167

.LBB0_245:
	s_or_b64 exec, exec, s[76:77]
	s_waitcnt vmcnt(0) lgkmcnt(0)
	s_barrier
	s_mov_b64 s[4:5], exec
	v_readlane_b32 s0, v255, 30
	v_readlane_b32 s1, v255, 31
	s_and_b64 s[0:1], s[4:5], s[0:1]
	s_mov_b64 exec, s[0:1]
	s_cbranch_execz .Lgs4_done
	s_mov_b64 exec, 1
	v_readlane_b32 s6, v255, 40
	v_readlane_b32 s7, v255, 41
	s_getreg_b32 s8, hwreg(HW_REG_XCC_ID)
	s_nop 3
	s_add_u32 s6, s6, 0x2480000
	s_addc_u32 s7, s7, 0
	s_and_b32 s8, s8, 7
	s_lshl_b32 s8, s8, 8
	v_mov_b32_e32 v0, s8
	v_mov_b32_e32 v2, 1
	v_mov_b32_e32 v3, 0x23ff8
	s_nop 1
	ds_read_b32 v3, v3
	global_atomic_add v2, v0, v2, s[6:7] sc0
	s_waitcnt vmcnt(0) lgkmcnt(0)
	v_readfirstlane_b32 s9, v2
	v_readfirstlane_b32 s10, v3
	s_and_b32 s9, s9, 31
	s_add_u32 s10, s10, 8
	s_cmp_lg_u32 s9, 31
	s_cbranch_scc1 .Lgs4_poll
	buffer_wbl2 sc1
	v_mov_b32_e32 v2, 1
	v_mov_b32_e32 v3, 0
	s_waitcnt vmcnt(0)
	global_atomic_add v3, v2, s[6:7] offset:2048
	global_atomic_add v3, v2, s[6:7] offset:2304
	global_atomic_add v3, v2, s[6:7] offset:2560
	global_atomic_add v3, v2, s[6:7] offset:2816
	global_atomic_add v3, v2, s[6:7] offset:3072
	global_atomic_add v3, v2, s[6:7] offset:3328
	global_atomic_add v3, v2, s[6:7] offset:3584
	global_atomic_add v3, v2, s[6:7] offset:3840

.LBB0_307:
	s_waitcnt vmcnt(0) lgkmcnt(0)
	s_barrier
	s_mov_b64 s[4:5], exec
	v_readlane_b32 s0, v255, 30
	v_readlane_b32 s1, v255, 31
	v_readlane_b32 s64, v255, 43
	v_readlane_b32 s65, v255, 44
	v_readlane_b32 s66, v255, 45
	v_readlane_b32 s67, v255, 46
	v_readlane_b32 s68, v255, 47
	v_readlane_b32 s69, v255, 48
	v_readlane_b32 s70, v255, 49
	v_readlane_b32 s71, v255, 50
	v_readlane_b32 s72, v255, 51
	v_readlane_b32 s73, v255, 52
	v_readlane_b32 s74, v255, 53
	v_readlane_b32 s75, v255, 54
	v_readlane_b32 s76, v255, 55
	v_readlane_b32 s77, v255, 56
	v_readlane_b32 s78, v255, 57
	v_readlane_b32 s79, v255, 58
	s_and_b64 s[0:1], s[4:5], s[0:1]
	s_mov_b64 exec, s[0:1]
	s_cbranch_execz .Lgs5_done
	s_mov_b64 exec, 1
	v_readlane_b32 s6, v255, 40
	v_readlane_b32 s7, v255, 41
	s_getreg_b32 s8, hwreg(HW_REG_XCC_ID)
	s_nop 3
	s_add_u32 s6, s6, 0x2480000
	s_addc_u32 s7, s7, 0
	s_and_b32 s8, s8, 7
	s_lshl_b32 s8, s8, 8
	v_mov_b32_e32 v0, s8
	v_mov_b32_e32 v2, 1
	v_mov_b32_e32 v3, 0x23ff8
	s_nop 1
	ds_read_b32 v3, v3
	global_atomic_add v2, v0, v2, s[6:7] sc0
	s_waitcnt vmcnt(0) lgkmcnt(0)
	v_readfirstlane_b32 s9, v2
	v_readfirstlane_b32 s10, v3
	s_and_b32 s9, s9, 31
	s_add_u32 s10, s10, 8
	s_cmp_lg_u32 s9, 31
	s_cbranch_scc1 .Lgs5_poll
	buffer_wbl2 sc1
	v_mov_b32_e32 v2, 1
	v_mov_b32_e32 v3, 0
	s_waitcnt vmcnt(0)
	global_atomic_add v3, v2, s[6:7] offset:2048
	global_atomic_add v3, v2, s[6:7] offset:2304
	global_atomic_add v3, v2, s[6:7] offset:2560
	global_atomic_add v3, v2, s[6:7] offset:2816
	global_atomic_add v3, v2, s[6:7] offset:3072
	global_atomic_add v3, v2, s[6:7] offset:3328
	global_atomic_add v3, v2, s[6:7] offset:3584
	global_atomic_add v3, v2, s[6:7] offset:3840
